# phase 0 weight transpose: nt (non-temporal) hint on the read-once f32 weight loads
# speedup vs baseline: 1.0122x; 1.0122x over previous
; __device__ __forceinline__ unsigned pk_bf16(float lo, float hi) { unsigned r; asm("v_cvt_pk_bf16_f32 %0, %1, %2" : "=v"(r) : "v"(lo), "v"(hi)); return r; }
; __device__ __forceinline__ void tr_cvt(const float* __restrict__ src, int K, int N, u16* __restrict__ dst, int& base, float* tile) {
;     ...
;     for (int t = start; t < nt; t += G) {
;         const int k0 = (t / tn) << 6, n0 = (t % tn) << 7;
;         __syncthreads();
;         {
;             const int r = tid >> 5, c = (tid & 31) << 2;
;             f32x4 v[4];
; #pragma unroll
;             for (int q = 0; q < 4; ++q) v[q] = *(const f32x4*)(src + (size_t)(k0 + r + q * 16) * N + n0 + c);
; #pragma unroll
;             for (int q = 0; q < 4; ++q)
; #pragma unroll
;                 for (int e = 0; e < 4; ++e) tile[(r + q * 16) * 129 + c + e] = v[q][e];
;         }
;         __syncthreads();
;         {
;             const int n = tid >> 2, k16 = (tid & 3) << 4;
;             float v[16];
; #pragma unroll
;             for (int e = 0; e < 16; ++e) v[e] = tile[(k16 + e) * 129 + n];
;             u32x4 w0, w1;
;             w0.x = pk_bf16(v[0], v[1]); w0.y = pk_bf16(v[2], v[3]); w0.z = pk_bf16(v[4], v[5]); w0.w = pk_bf16(v[6], v[7]);
;             w1.x = pk_bf16(v[8], v[9]); w1.y = pk_bf16(v[10], v[11]); w1.z = pk_bf16(v[12], v[13]); w1.w = pk_bf16(v[14], v[15]);
;             u16* dp = dst + (size_t)(n0 + n) * K + k0 + k16;
;             *(u32x4*)dp = w0; *(u32x4*)(dp + 8) = w1;
;         }
.LBB0_15:
	s_mul_hi_i32 s12, s78, 0x8c08c08d
	s_add_i32 s12, s12, s78
	s_lshr_b32 s13, s12, 31
	s_ashr_i32 s12, s12, 6
	s_add_i32 s13, s12, s13
	s_lshl_b32 s12, s13, 6
	s_mulk_i32 s13, 0xc580
	s_add_i32 s34, s79, s13
	s_ashr_i32 s35, s34, 31
	v_add_u32_e32 v38, s12, v2
	v_lshl_add_u64 v[36:37], s[34:35], 2, v[6:7]
	v_mad_i64_i32 v[24:25], s[84:85], v38, s23, v[36:37]
	s_barrier
	global_load_dwordx4 v[24:27], v[24:25], off nt
	v_add_u32_e32 v28, 16, v38
	v_mad_i64_i32 v[28:29], s[84:85], v28, s23, v[36:37]
	global_load_dwordx4 v[28:31], v[28:29], off nt
	v_add_u32_e32 v32, 32, v38
	v_mad_i64_i32 v[32:33], s[84:85], v32, s23, v[36:37]
	global_load_dwordx4 v[32:35], v[32:33], off nt
	v_add_u32_e32 v38, 48, v38
	v_mad_i64_i32 v[36:37], s[84:85], v38, s23, v[36:37]
	global_load_dwordx4 v[36:39], v[36:37], off nt
	s_ashr_i32 s13, s12, 31
	s_add_i32 s78, s78, s33
	s_add_i32 s79, s79, s82
	s_cmpk_lt_i32 s78, 0xea0
	s_waitcnt vmcnt(3)
	ds_write2_b32 v9, v24, v25 offset1:1
	ds_write2_b32 v9, v26, v27 offset0:2 offset1:3
	s_waitcnt vmcnt(2)
	ds_write2_b32 v10, v28, v29 offset1:1
	ds_write2_b32 v11, v30, v31 offset1:1
	s_waitcnt vmcnt(1)
	ds_write2_b32 v12, v32, v33 offset1:1
	ds_write2_b32 v13, v34, v35 offset1:1
	s_waitcnt vmcnt(0)
	ds_write2_b32 v14, v36, v37 offset1:1
	ds_write2_b32 v15, v38, v39 offset1:1
	s_waitcnt lgkmcnt(0)
	s_barrier
	ds_read2_b32 v[24:25], v16 offset1:129
	ds_read2_b32 v[26:27], v17 offset0:2 offset1:131
	s_waitcnt lgkmcnt(1)
	v_cvt_pk_bf16_f32 v24, v24, v25
	s_waitcnt lgkmcnt(0)
	v_cvt_pk_bf16_f32 v25, v26, v27
	ds_read2_b32 v[26:27], v18 offset0:4 offset1:133
	ds_read2_b32 v[28:29], v19 offset0:6 offset1:135
	s_waitcnt lgkmcnt(1)
	v_cvt_pk_bf16_f32 v26, v26, v27
	s_waitcnt lgkmcnt(0)
	v_cvt_pk_bf16_f32 v27, v28, v29
	ds_read2_b32 v[28:29], v20 offset0:8 offset1:137
	ds_read2_b32 v[30:31], v21 offset0:10 offset1:139
	s_waitcnt lgkmcnt(1)
	v_cvt_pk_bf16_f32 v28, v28, v29
	s_waitcnt lgkmcnt(0)
	v_cvt_pk_bf16_f32 v29, v30, v31
	ds_read2_b32 v[30:31], v22 offset0:12 offset1:141
	ds_read2_b32 v[32:33], v23 offset0:14 offset1:143
	s_waitcnt lgkmcnt(1)
	v_cvt_pk_bf16_f32 v30, v30, v31
	s_waitcnt lgkmcnt(0)
	v_cvt_pk_bf16_f32 v31, v32, v33
	v_add_u32_e32 v32, s34, v8
	v_ashrrev_i32_e32 v33, 31, v32
	v_lshlrev_b64 v[32:33], 12, v[32:33]
	v_lshl_add_u64 v[32:33], s[10:11], 0, v[32:33]
	v_lshl_add_u64 v[32:33], s[12:13], 1, v[32:33]
	v_lshl_add_u64 v[32:33], v[32:33], 0, v[4:5]
	global_store_dwordx4 v[32:33], v[24:27], off
	global_store_dwordx4 v[32:33], v[28:31], off offset:16
	s_cbranch_scc1 .LBB0_15

; __device__ __forceinline__ unsigned pk_bf16(float lo, float hi) { unsigned r; asm("v_cvt_pk_bf16_f32 %0, %1, %2" : "=v"(r) : "v"(lo), "v"(hi)); return r; }
; __device__ __forceinline__ void tr_cvt(const float* __restrict__ src, int K, int N, u16* __restrict__ dst, int& base, float* tile) {
;     ...
;     for (int t = start; t < nt; t += G) {
;         const int k0 = (t / tn) << 6, n0 = (t % tn) << 7;
;         __syncthreads();
;         {
;             const int r = tid >> 5, c = (tid & 31) << 2;
;             f32x4 v[4];
; #pragma unroll
;             for (int q = 0; q < 4; ++q) v[q] = *(const f32x4*)(src + (size_t)(k0 + r + q * 16) * N + n0 + c);
; #pragma unroll
;             for (int q = 0; q < 4; ++q)
; #pragma unroll
;                 for (int e = 0; e < 4; ++e) tile[(r + q * 16) * 129 + c + e] = v[q][e];
;         }
;         __syncthreads();
;         {
;             const int n = tid >> 2, k16 = (tid & 3) << 4;
;             float v[16];
; #pragma unroll
;             for (int e = 0; e < 16; ++e) v[e] = tile[(k16 + e) * 129 + n];
;             u32x4 w0, w1;
;             w0.x = pk_bf16(v[0], v[1]); w0.y = pk_bf16(v[2], v[3]); w0.z = pk_bf16(v[4], v[5]); w0.w = pk_bf16(v[6], v[7]);
;             w1.x = pk_bf16(v[8], v[9]); w1.y = pk_bf16(v[10], v[11]); w1.z = pk_bf16(v[12], v[13]); w1.w = pk_bf16(v[14], v[15]);
;             u16* dp = dst + (size_t)(n0 + n) * K + k0 + k16;
;             *(u32x4*)dp = w0; *(u32x4*)(dp + 8) = w1;
;         }
.LBB0_18:
	s_ashr_i32 s34, s82, 31
	s_lshr_b32 s34, s34, 28
	s_add_i32 s34, s82, s34
	s_ashr_i32 s35, s34, 4
	s_lshl_b32 s34, s35, 6
	s_lshl_b32 s35, s35, 11
	s_sub_i32 s78, s11, s35
	v_add_u32_e32 v16, s34, v2
	s_ashr_i32 s79, s78, 31
	v_ashrrev_i32_e32 v17, 31, v16
	v_lshl_add_u64 v[18:19], s[78:79], 2, v[6:7]
	v_lshlrev_b64 v[16:17], 13, v[16:17]
	v_lshl_add_u64 v[28:29], v[18:19], 0, v[16:17]
	v_add_co_u32_e32 v20, vcc, s24, v28
	s_nop 1
	v_addc_co_u32_e32 v21, vcc, 0, v29, vcc
	v_add_co_u32_e32 v24, vcc, s25, v28
	s_barrier
	s_nop 0
	v_addc_co_u32_e32 v25, vcc, 0, v29, vcc
	global_load_dwordx4 v[16:19], v[28:29], off nt
	v_add_co_u32_e32 v28, vcc, s27, v28
	global_load_dwordx4 v[20:23], v[20:21], off nt
	s_nop 0
	v_addc_co_u32_e32 v29, vcc, 0, v29, vcc
	global_load_dwordx4 v[28:31], v[28:29], off nt
	v_add_u32_e32 v15, 0x60c0, v9
	global_load_dwordx4 v[24:27], v[24:25], off nt
	s_ashr_i32 s35, s34, 31
	s_add_i32 s82, s82, s33
	s_add_i32 s11, s11, s83
	s_cmpk_lt_i32 s82, 0x100
	s_waitcnt vmcnt(3)
	ds_write2_b32 v9, v16, v17 offset1:1
	ds_write2_b32 v9, v18, v19 offset0:2 offset1:3
	s_waitcnt vmcnt(2)
	ds_write2_b32 v11, v20, v21 offset1:1
	ds_write2_b32 v12, v22, v23 offset1:1
	s_waitcnt vmcnt(0)
	ds_write2_b32 v13, v24, v25 offset1:1
	ds_write2_b32 v14, v26, v27 offset1:1
	ds_write2_b32 v15, v28, v29 offset1:1
	v_add_u32_e32 v15, 0x60c8, v9
	ds_write2_b32 v15, v30, v31 offset1:1
	v_add_u32_e32 v15, 0x400, v10
	s_waitcnt lgkmcnt(0)
	s_barrier
	ds_read2_b32 v[16:17], v10 offset1:129
	ds_read2_b32 v[18:19], v15 offset0:2 offset1:131
	v_add_u32_e32 v15, 0x800, v10
	s_waitcnt lgkmcnt(1)
	v_cvt_pk_bf16_f32 v16, v16, v17
	s_waitcnt lgkmcnt(0)
	v_cvt_pk_bf16_f32 v17, v18, v19
	ds_read2_b32 v[18:19], v15 offset0:4 offset1:133
	v_add_u32_e32 v15, 0xc00, v10
	ds_read2_b32 v[20:21], v15 offset0:6 offset1:135
	v_add_u32_e32 v15, 0x1000, v10
	s_waitcnt lgkmcnt(1)
	v_cvt_pk_bf16_f32 v18, v18, v19
	s_waitcnt lgkmcnt(0)
	v_cvt_pk_bf16_f32 v19, v20, v21
	ds_read2_b32 v[20:21], v15 offset0:8 offset1:137
	v_add_u32_e32 v15, 0x1400, v10
	ds_read2_b32 v[22:23], v15 offset0:10 offset1:139
	v_add_u32_e32 v15, 0x1800, v10
	s_waitcnt lgkmcnt(1)
	v_cvt_pk_bf16_f32 v20, v20, v21
	s_waitcnt lgkmcnt(0)
	v_cvt_pk_bf16_f32 v21, v22, v23
	ds_read2_b32 v[22:23], v15 offset0:12 offset1:141
	v_add_u32_e32 v15, 0x1c00, v10
	ds_read2_b32 v[24:25], v15 offset0:14 offset1:143
	s_waitcnt lgkmcnt(1)
	v_cvt_pk_bf16_f32 v22, v22, v23
	s_waitcnt lgkmcnt(0)
	v_cvt_pk_bf16_f32 v23, v24, v25
	v_add_u32_e32 v24, s78, v8
	v_ashrrev_i32_e32 v25, 31, v24
	v_lshlrev_b64 v[24:25], 11, v[24:25]
	v_lshl_add_u64 v[24:25], s[12:13], 0, v[24:25]
	v_lshl_add_u64 v[24:25], s[34:35], 1, v[24:25]
	v_lshl_add_u64 v[24:25], v[24:25], 0, v[4:5]
	global_store_dwordx4 v[24:25], v[16:19], off
	global_store_dwordx4 v[24:25], v[20:23], off offset:16
	s_cbranch_scc1 .LBB0_18

; __device__ __forceinline__ unsigned pk_bf16(float lo, float hi) { unsigned r; asm("v_cvt_pk_bf16_f32 %0, %1, %2" : "=v"(r) : "v"(lo), "v"(hi)); return r; }
; __device__ __forceinline__ void tr_cvt(const float* __restrict__ src, int K, int N, u16* __restrict__ dst, int& base, float* tile) {
;     ...
;     for (int t = start; t < nt; t += G) {
;         const int k0 = (t / tn) << 6, n0 = (t % tn) << 7;
;         __syncthreads();
;         {
;             const int r = tid >> 5, c = (tid & 31) << 2;
;             f32x4 v[4];
; #pragma unroll
;             for (int q = 0; q < 4; ++q) v[q] = *(const f32x4*)(src + (size_t)(k0 + r + q * 16) * N + n0 + c);
; #pragma unroll
;             for (int q = 0; q < 4; ++q)
; #pragma unroll
;                 for (int e = 0; e < 4; ++e) tile[(r + q * 16) * 129 + c + e] = v[q][e];
;         }
;         __syncthreads();
;         {
;             const int n = tid >> 2, k16 = (tid & 3) << 4;
;             float v[16];
; #pragma unroll
;             for (int e = 0; e < 16; ++e) v[e] = tile[(k16 + e) * 129 + n];
;             u32x4 w0, w1;
;             w0.x = pk_bf16(v[0], v[1]); w0.y = pk_bf16(v[2], v[3]); w0.z = pk_bf16(v[4], v[5]); w0.w = pk_bf16(v[6], v[7]);
;             w1.x = pk_bf16(v[8], v[9]); w1.y = pk_bf16(v[10], v[11]); w1.z = pk_bf16(v[12], v[13]); w1.w = pk_bf16(v[14], v[15]);
;             u16* dp = dst + (size_t)(n0 + n) * K + k0 + k16;
;             *(u32x4*)dp = w0; *(u32x4*)(dp + 8) = w1;
;         }
.LBB0_21:
	s_ashr_i32 s34, s11, 31
	s_lshr_b32 s34, s34, 28
	s_add_i32 s34, s11, s34
	s_ashr_i32 s35, s34, 4
	s_lshl_b32 s34, s35, 6
	s_lshl_b32 s35, s35, 11
	s_sub_i32 s78, s82, s35
	v_add_u32_e32 v12, s34, v2
	s_ashr_i32 s79, s78, 31
	v_ashrrev_i32_e32 v13, 31, v12
	v_lshl_add_u64 v[14:15], s[78:79], 2, v[6:7]
	v_lshlrev_b64 v[12:13], 13, v[12:13]
	v_lshl_add_u64 v[24:25], v[14:15], 0, v[12:13]
	v_add_co_u32_e32 v16, vcc, s24, v24
	s_nop 1
	v_addc_co_u32_e32 v17, vcc, 0, v25, vcc
	s_barrier
	global_load_dwordx4 v[12:15], v[24:25], off nt
	v_add_co_u32_e32 v20, vcc, s25, v24
	global_load_dwordx4 v[16:19], v[16:17], off nt
	s_nop 0
	v_addc_co_u32_e32 v21, vcc, 0, v25, vcc
	global_load_dwordx4 v[20:23], v[20:21], off nt
	v_add_co_u32_e32 v24, vcc, s27, v24
	v_add_u32_e32 v11, 0x2040, v9
	s_nop 0
	v_addc_co_u32_e32 v25, vcc, 0, v25, vcc
	global_load_dwordx4 v[24:27], v[24:25], off nt
	s_ashr_i32 s35, s34, 31
	s_add_i32 s11, s11, s33
	s_add_i32 s82, s82, s83
	s_cmpk_lt_i32 s11, 0x100
	s_waitcnt vmcnt(3)
	ds_write2_b32 v9, v12, v13 offset1:1
	ds_write2_b32 v9, v14, v15 offset0:2 offset1:3
	s_waitcnt vmcnt(2)
	ds_write2_b32 v11, v16, v17 offset1:1
	v_add_u32_e32 v11, 0x2048, v9
	ds_write2_b32 v11, v18, v19 offset1:1
	v_add_u32_e32 v11, 0x4080, v9
	s_waitcnt vmcnt(1)
	ds_write2_b32 v11, v20, v21 offset1:1
	v_add_u32_e32 v11, 0x4088, v9
	ds_write2_b32 v11, v22, v23 offset1:1
	v_add_u32_e32 v11, 0x60c0, v9
	s_waitcnt vmcnt(0)
	ds_write2_b32 v11, v24, v25 offset1:1
	v_add_u32_e32 v11, 0x60c8, v9
	ds_write2_b32 v11, v26, v27 offset1:1
	v_add_u32_e32 v11, 0x400, v10
	s_waitcnt lgkmcnt(0)
	s_barrier
	ds_read2_b32 v[12:13], v10 offset1:129
	ds_read2_b32 v[14:15], v11 offset0:2 offset1:131
	v_add_u32_e32 v11, 0x800, v10
	s_waitcnt lgkmcnt(1)
	v_cvt_pk_bf16_f32 v12, v12, v13
	s_waitcnt lgkmcnt(0)
	v_cvt_pk_bf16_f32 v13, v14, v15
	ds_read2_b32 v[14:15], v11 offset0:4 offset1:133
	v_add_u32_e32 v11, 0xc00, v10
	ds_read2_b32 v[16:17], v11 offset0:6 offset1:135
	v_add_u32_e32 v11, 0x1000, v10
	s_waitcnt lgkmcnt(1)
	v_cvt_pk_bf16_f32 v14, v14, v15
	s_waitcnt lgkmcnt(0)
	v_cvt_pk_bf16_f32 v15, v16, v17
	ds_read2_b32 v[16:17], v11 offset0:8 offset1:137
	v_add_u32_e32 v11, 0x1400, v10
	ds_read2_b32 v[18:19], v11 offset0:10 offset1:139
	v_add_u32_e32 v11, 0x1800, v10
	s_waitcnt lgkmcnt(1)
	v_cvt_pk_bf16_f32 v16, v16, v17
	s_waitcnt lgkmcnt(0)
	v_cvt_pk_bf16_f32 v17, v18, v19
	ds_read2_b32 v[18:19], v11 offset0:12 offset1:141
	v_add_u32_e32 v11, 0x1c00, v10
	ds_read2_b32 v[20:21], v11 offset0:14 offset1:143
	s_waitcnt lgkmcnt(1)
	v_cvt_pk_bf16_f32 v18, v18, v19
	s_waitcnt lgkmcnt(0)
	v_cvt_pk_bf16_f32 v19, v20, v21
	v_add_u32_e32 v20, s78, v8
	v_ashrrev_i32_e32 v21, 31, v20
	v_lshlrev_b64 v[20:21], 11, v[20:21]
	v_lshl_add_u64 v[20:21], s[12:13], 0, v[20:21]
	v_lshl_add_u64 v[20:21], s[34:35], 1, v[20:21]
	v_lshl_add_u64 v[20:21], v[20:21], 0, v[4:5]
	global_store_dwordx4 v[20:21], v[12:15], off
	global_store_dwordx4 v[20:21], v[16:19], off offset:16
	s_cbranch_scc1 .LBB0_21

; __device__ __forceinline__ unsigned pk_bf16(float lo, float hi) { unsigned r; asm("v_cvt_pk_bf16_f32 %0, %1, %2" : "=v"(r) : "v"(lo), "v"(hi)); return r; }
; __device__ __forceinline__ void tr_cvt(const float* __restrict__ src, int K, int N, u16* __restrict__ dst, int& base, float* tile) {
;     ...
;     for (int t = start; t < nt; t += G) {
;         const int k0 = (t / tn) << 6, n0 = (t % tn) << 7;
;         __syncthreads();
;         {
;             const int r = tid >> 5, c = (tid & 31) << 2;
;             f32x4 v[4];
; #pragma unroll
;             for (int q = 0; q < 4; ++q) v[q] = *(const f32x4*)(src + (size_t)(k0 + r + q * 16) * N + n0 + c);
; #pragma unroll
;             for (int q = 0; q < 4; ++q)
; #pragma unroll
;                 for (int e = 0; e < 4; ++e) tile[(r + q * 16) * 129 + c + e] = v[q][e];
;         }
;         __syncthreads();
;         {
;             const int n = tid >> 2, k16 = (tid & 3) << 4;
;             float v[16];
; #pragma unroll
;             for (int e = 0; e < 16; ++e) v[e] = tile[(k16 + e) * 129 + n];
;             u32x4 w0, w1;
;             w0.x = pk_bf16(v[0], v[1]); w0.y = pk_bf16(v[2], v[3]); w0.z = pk_bf16(v[4], v[5]); w0.w = pk_bf16(v[6], v[7]);
;             w1.x = pk_bf16(v[8], v[9]); w1.y = pk_bf16(v[10], v[11]); w1.z = pk_bf16(v[12], v[13]); w1.w = pk_bf16(v[14], v[15]);
;             u16* dp = dst + (size_t)(n0 + n) * K + k0 + k16;
;             *(u32x4*)dp = w0; *(u32x4*)(dp + 8) = w1;
;         }
.LBB0_24:
	s_ashr_i32 s12, s78, 31
	s_lshr_b32 s12, s12, 28
	s_add_i32 s12, s78, s12
	s_ashr_i32 s13, s12, 4
	s_lshl_b32 s12, s13, 6
	s_lshl_b32 s13, s13, 11
	s_sub_i32 s34, s79, s13
	v_add_u32_e32 v12, s12, v2
	s_ashr_i32 s35, s34, 31
	v_ashrrev_i32_e32 v13, 31, v12
	v_lshl_add_u64 v[14:15], s[34:35], 2, v[6:7]
	v_lshlrev_b64 v[12:13], 13, v[12:13]
	v_lshl_add_u64 v[24:25], v[14:15], 0, v[12:13]
	v_add_co_u32_e32 v16, vcc, s24, v24
	s_nop 1
	v_addc_co_u32_e32 v17, vcc, 0, v25, vcc
	s_barrier
	global_load_dwordx4 v[12:15], v[24:25], off nt
	v_add_co_u32_e32 v20, vcc, s25, v24
	global_load_dwordx4 v[16:19], v[16:17], off nt
	s_nop 0
	v_addc_co_u32_e32 v21, vcc, 0, v25, vcc
	global_load_dwordx4 v[20:23], v[20:21], off nt
	v_add_co_u32_e32 v24, vcc, s27, v24
	v_add_u32_e32 v11, 0x2040, v9
	s_nop 0
	v_addc_co_u32_e32 v25, vcc, 0, v25, vcc
	global_load_dwordx4 v[24:27], v[24:25], off nt
	s_ashr_i32 s13, s12, 31
	s_add_i32 s78, s78, s33
	s_add_i32 s79, s79, s82
	s_cmpk_lt_i32 s78, 0x100
	s_waitcnt vmcnt(3)
	ds_write2_b32 v9, v12, v13 offset1:1
	ds_write2_b32 v9, v14, v15 offset0:2 offset1:3
	s_waitcnt vmcnt(2)
	ds_write2_b32 v11, v16, v17 offset1:1
	v_add_u32_e32 v11, 0x2048, v9
	ds_write2_b32 v11, v18, v19 offset1:1
	v_add_u32_e32 v11, 0x4080, v9
	s_waitcnt vmcnt(1)
	ds_write2_b32 v11, v20, v21 offset1:1
	v_add_u32_e32 v11, 0x4088, v9
	ds_write2_b32 v11, v22, v23 offset1:1
	v_add_u32_e32 v11, 0x60c0, v9
	s_waitcnt vmcnt(0)
	ds_write2_b32 v11, v24, v25 offset1:1
	v_add_u32_e32 v11, 0x60c8, v9
	ds_write2_b32 v11, v26, v27 offset1:1
	v_add_u32_e32 v11, 0x400, v10
	s_waitcnt lgkmcnt(0)
	s_barrier
	ds_read2_b32 v[12:13], v10 offset1:129
	ds_read2_b32 v[14:15], v11 offset0:2 offset1:131
	v_add_u32_e32 v11, 0x800, v10
	s_waitcnt lgkmcnt(1)
	v_cvt_pk_bf16_f32 v12, v12, v13
	s_waitcnt lgkmcnt(0)
	v_cvt_pk_bf16_f32 v13, v14, v15
	ds_read2_b32 v[14:15], v11 offset0:4 offset1:133
	v_add_u32_e32 v11, 0xc00, v10
	ds_read2_b32 v[16:17], v11 offset0:6 offset1:135
	v_add_u32_e32 v11, 0x1000, v10
	s_waitcnt lgkmcnt(1)
	v_cvt_pk_bf16_f32 v14, v14, v15
	s_waitcnt lgkmcnt(0)
	v_cvt_pk_bf16_f32 v15, v16, v17
	ds_read2_b32 v[16:17], v11 offset0:8 offset1:137
	v_add_u32_e32 v11, 0x1400, v10
	ds_read2_b32 v[18:19], v11 offset0:10 offset1:139
	v_add_u32_e32 v11, 0x1800, v10
	s_waitcnt lgkmcnt(1)
	v_cvt_pk_bf16_f32 v16, v16, v17
	s_waitcnt lgkmcnt(0)
	v_cvt_pk_bf16_f32 v17, v18, v19
	ds_read2_b32 v[18:19], v11 offset0:12 offset1:141
	v_add_u32_e32 v11, 0x1c00, v10
	ds_read2_b32 v[20:21], v11 offset0:14 offset1:143
	s_waitcnt lgkmcnt(1)
	v_cvt_pk_bf16_f32 v18, v18, v19
	s_waitcnt lgkmcnt(0)
	v_cvt_pk_bf16_f32 v19, v20, v21
	v_add_u32_e32 v20, s34, v8
	v_ashrrev_i32_e32 v21, 31, v20
	v_lshlrev_b64 v[20:21], 11, v[20:21]
	v_lshl_add_u64 v[20:21], s[10:11], 0, v[20:21]
	v_lshl_add_u64 v[20:21], s[12:13], 1, v[20:21]
	v_lshl_add_u64 v[20:21], v[20:21], 0, v[4:5]
	global_store_dwordx4 v[20:21], v[12:15], off
	global_store_dwordx4 v[20:21], v[16:19], off offset:16
	s_cbranch_scc1 .LBB0_24

; __device__ __forceinline__ unsigned pk_bf16(float lo, float hi) { unsigned r; asm("v_cvt_pk_bf16_f32 %0, %1, %2" : "=v"(r) : "v"(lo), "v"(hi)); return r; }
; __device__ __forceinline__ void tr_cvt(const float* __restrict__ src, int K, int N, u16* __restrict__ dst, int& base, float* tile) {
;     ...
;     for (int t = start; t < nt; t += G) {
;         const int k0 = (t / tn) << 6, n0 = (t % tn) << 7;
;         __syncthreads();
;         {
;             const int r = tid >> 5, c = (tid & 31) << 2;
;             f32x4 v[4];
; #pragma unroll
;             for (int q = 0; q < 4; ++q) v[q] = *(const f32x4*)(src + (size_t)(k0 + r + q * 16) * N + n0 + c);
; #pragma unroll
;             for (int q = 0; q < 4; ++q)
; #pragma unroll
;                 for (int e = 0; e < 4; ++e) tile[(r + q * 16) * 129 + c + e] = v[q][e];
;         }
;         __syncthreads();
;         {
;             const int n = tid >> 2, k16 = (tid & 3) << 4;
;             float v[16];
; #pragma unroll
;             for (int e = 0; e < 16; ++e) v[e] = tile[(k16 + e) * 129 + n];
;             u32x4 w0, w1;
;             w0.x = pk_bf16(v[0], v[1]); w0.y = pk_bf16(v[2], v[3]); w0.z = pk_bf16(v[4], v[5]); w0.w = pk_bf16(v[6], v[7]);
;             w1.x = pk_bf16(v[8], v[9]); w1.y = pk_bf16(v[10], v[11]); w1.z = pk_bf16(v[12], v[13]); w1.w = pk_bf16(v[14], v[15]);
;             u16* dp = dst + (size_t)(n0 + n) * K + k0 + k16;
;             *(u32x4*)dp = w0; *(u32x4*)(dp + 8) = w1;
;         }
.LBB0_27:
	s_ashr_i32 s12, s78, 31
	s_lshr_b32 s12, s12, 28
	s_add_i32 s12, s78, s12
	s_ashr_i32 s13, s12, 4
	s_lshl_b32 s12, s13, 6
	s_lshl_b32 s13, s13, 11
	s_sub_i32 s34, s79, s13
	v_add_u32_e32 v12, s12, v2
	s_ashr_i32 s35, s34, 31
	v_ashrrev_i32_e32 v13, 31, v12
	v_lshl_add_u64 v[14:15], s[34:35], 2, v[6:7]
	v_lshlrev_b64 v[12:13], 13, v[12:13]
	v_lshl_add_u64 v[24:25], v[14:15], 0, v[12:13]
	v_add_co_u32_e32 v16, vcc, s24, v24
	s_nop 1
	v_addc_co_u32_e32 v17, vcc, 0, v25, vcc
	s_barrier
	global_load_dwordx4 v[12:15], v[24:25], off nt
	v_add_co_u32_e32 v20, vcc, s25, v24
	global_load_dwordx4 v[16:19], v[16:17], off nt
	s_nop 0
	v_addc_co_u32_e32 v21, vcc, 0, v25, vcc
	global_load_dwordx4 v[20:23], v[20:21], off nt
	v_add_co_u32_e32 v24, vcc, s27, v24
	v_add_u32_e32 v11, 0x2040, v9
	s_nop 0
	v_addc_co_u32_e32 v25, vcc, 0, v25, vcc
	global_load_dwordx4 v[24:27], v[24:25], off nt
	s_ashr_i32 s13, s12, 31
	s_add_i32 s78, s78, s33
	s_add_i32 s79, s79, s82
	s_cmpk_lt_i32 s78, 0x200
	s_waitcnt vmcnt(3)
	ds_write2_b32 v9, v12, v13 offset1:1
	ds_write2_b32 v9, v14, v15 offset0:2 offset1:3
	s_waitcnt vmcnt(2)
	ds_write2_b32 v11, v16, v17 offset1:1
	v_add_u32_e32 v11, 0x2048, v9
	ds_write2_b32 v11, v18, v19 offset1:1
	v_add_u32_e32 v11, 0x4080, v9
	s_waitcnt vmcnt(1)
	ds_write2_b32 v11, v20, v21 offset1:1
	v_add_u32_e32 v11, 0x4088, v9
	ds_write2_b32 v11, v22, v23 offset1:1
	v_add_u32_e32 v11, 0x60c0, v9
	s_waitcnt vmcnt(0)
	ds_write2_b32 v11, v24, v25 offset1:1
	v_add_u32_e32 v11, 0x60c8, v9
	ds_write2_b32 v11, v26, v27 offset1:1
	v_add_u32_e32 v11, 0x400, v10
	s_waitcnt lgkmcnt(0)
	s_barrier
	ds_read2_b32 v[12:13], v10 offset1:129
	ds_read2_b32 v[14:15], v11 offset0:2 offset1:131
	v_add_u32_e32 v11, 0x800, v10
	s_waitcnt lgkmcnt(1)
	v_cvt_pk_bf16_f32 v12, v12, v13
	s_waitcnt lgkmcnt(0)
	v_cvt_pk_bf16_f32 v13, v14, v15
	ds_read2_b32 v[14:15], v11 offset0:4 offset1:133
	v_add_u32_e32 v11, 0xc00, v10
	ds_read2_b32 v[16:17], v11 offset0:6 offset1:135
	v_add_u32_e32 v11, 0x1000, v10
	s_waitcnt lgkmcnt(1)
	v_cvt_pk_bf16_f32 v14, v14, v15
	s_waitcnt lgkmcnt(0)
	v_cvt_pk_bf16_f32 v15, v16, v17
	ds_read2_b32 v[16:17], v11 offset0:8 offset1:137
	v_add_u32_e32 v11, 0x1400, v10
	ds_read2_b32 v[18:19], v11 offset0:10 offset1:139
	v_add_u32_e32 v11, 0x1800, v10
	s_waitcnt lgkmcnt(1)
	v_cvt_pk_bf16_f32 v16, v16, v17
	s_waitcnt lgkmcnt(0)
	v_cvt_pk_bf16_f32 v17, v18, v19
	ds_read2_b32 v[18:19], v11 offset0:12 offset1:141
	v_add_u32_e32 v11, 0x1c00, v10
	ds_read2_b32 v[20:21], v11 offset0:14 offset1:143
	s_waitcnt lgkmcnt(1)
	v_cvt_pk_bf16_f32 v18, v18, v19
	s_waitcnt lgkmcnt(0)
	v_cvt_pk_bf16_f32 v19, v20, v21
	v_add_u32_e32 v20, s34, v8
	v_ashrrev_i32_e32 v21, 31, v20
	v_lshlrev_b64 v[20:21], 12, v[20:21]
	v_lshl_add_u64 v[20:21], s[10:11], 0, v[20:21]
	v_lshl_add_u64 v[20:21], s[12:13], 1, v[20:21]
	v_lshl_add_u64 v[20:21], v[20:21], 0, v[4:5]
	global_store_dwordx4 v[20:21], v[12:15], off
	global_store_dwordx4 v[20:21], v[16:19], off offset:16
	s_cbranch_scc1 .LBB0_27

; __device__ __forceinline__ unsigned pk_bf16(float lo, float hi) { unsigned r; asm("v_cvt_pk_bf16_f32 %0, %1, %2" : "=v"(r) : "v"(lo), "v"(hi)); return r; }
; __device__ __forceinline__ void tr_cvt(const float* __restrict__ src, int K, int N, u16* __restrict__ dst, int& base, float* tile) {
;     ...
;     for (int t = start; t < nt; t += G) {
;         const int k0 = (t / tn) << 6, n0 = (t % tn) << 7;
;         __syncthreads();
;         {
;             const int r = tid >> 5, c = (tid & 31) << 2;
;             f32x4 v[4];
; #pragma unroll
;             for (int q = 0; q < 4; ++q) v[q] = *(const f32x4*)(src + (size_t)(k0 + r + q * 16) * N + n0 + c);
; #pragma unroll
;             for (int q = 0; q < 4; ++q)
; #pragma unroll
;                 for (int e = 0; e < 4; ++e) tile[(r + q * 16) * 129 + c + e] = v[q][e];
;         }
;         __syncthreads();
;         {
;             const int n = tid >> 2, k16 = (tid & 3) << 4;
;             float v[16];
; #pragma unroll
;             for (int e = 0; e < 16; ++e) v[e] = tile[(k16 + e) * 129 + n];
;             u32x4 w0, w1;
;             w0.x = pk_bf16(v[0], v[1]); w0.y = pk_bf16(v[2], v[3]); w0.z = pk_bf16(v[4], v[5]); w0.w = pk_bf16(v[6], v[7]);
;             w1.x = pk_bf16(v[8], v[9]); w1.y = pk_bf16(v[10], v[11]); w1.z = pk_bf16(v[12], v[13]); w1.w = pk_bf16(v[14], v[15]);
;             u16* dp = dst + (size_t)(n0 + n) * K + k0 + k16;
;             *(u32x4*)dp = w0; *(u32x4*)(dp + 8) = w1;
;         }
.LBB0_30:
	s_lshr_b32 s34, s82, 31
	s_add_i32 s34, s82, s34
	s_ashr_i32 s35, s34, 1
	s_lshl_b32 s34, s35, 6
	s_lshl_b32 s35, s35, 8
	s_sub_i32 s78, s11, s35
	v_add_u32_e32 v12, s34, v2
	s_ashr_i32 s79, s78, 31
	v_ashrrev_i32_e32 v13, 31, v12
	v_lshl_add_u64 v[14:15], s[78:79], 2, v[6:7]
	v_lshlrev_b64 v[12:13], 10, v[12:13]
	v_lshl_add_u64 v[24:25], v[14:15], 0, v[12:13]
	v_add_co_u32_e32 v16, vcc, s28, v24
	s_nop 1
	v_addc_co_u32_e32 v17, vcc, 0, v25, vcc
	s_barrier
	global_load_dwordx4 v[12:15], v[24:25], off nt
	v_add_co_u32_e32 v20, vcc, s29, v24
	global_load_dwordx4 v[16:19], v[16:17], off nt
	s_nop 0
	v_addc_co_u32_e32 v21, vcc, 0, v25, vcc
	global_load_dwordx4 v[20:23], v[20:21], off nt
	v_add_co_u32_e32 v24, vcc, s30, v24
	v_add_u32_e32 v11, 0x2040, v9
	s_nop 0
	v_addc_co_u32_e32 v25, vcc, 0, v25, vcc
	global_load_dwordx4 v[24:27], v[24:25], off nt
	s_ashr_i32 s35, s34, 31
	s_add_i32 s82, s82, s33
	s_add_i32 s11, s11, s83
	s_cmp_lt_i32 s82, 8
	s_waitcnt vmcnt(3)
	ds_write2_b32 v9, v12, v13 offset1:1
	ds_write2_b32 v9, v14, v15 offset0:2 offset1:3
	s_waitcnt vmcnt(2)
	ds_write2_b32 v11, v16, v17 offset1:1
	v_add_u32_e32 v11, 0x2048, v9
	ds_write2_b32 v11, v18, v19 offset1:1
	v_add_u32_e32 v11, 0x4080, v9
	s_waitcnt vmcnt(1)
	ds_write2_b32 v11, v20, v21 offset1:1
	v_add_u32_e32 v11, 0x4088, v9
	ds_write2_b32 v11, v22, v23 offset1:1
	v_add_u32_e32 v11, 0x60c0, v9
	s_waitcnt vmcnt(0)
	ds_write2_b32 v11, v24, v25 offset1:1
	v_add_u32_e32 v11, 0x60c8, v9
	ds_write2_b32 v11, v26, v27 offset1:1
	v_add_u32_e32 v11, 0x400, v10
	s_waitcnt lgkmcnt(0)
	s_barrier
	ds_read2_b32 v[12:13], v10 offset1:129
	ds_read2_b32 v[14:15], v11 offset0:2 offset1:131
	v_add_u32_e32 v11, 0x800, v10
	s_waitcnt lgkmcnt(1)
	v_cvt_pk_bf16_f32 v12, v12, v13
	s_waitcnt lgkmcnt(0)
	v_cvt_pk_bf16_f32 v13, v14, v15
	ds_read2_b32 v[14:15], v11 offset0:4 offset1:133
	v_add_u32_e32 v11, 0xc00, v10
	ds_read2_b32 v[16:17], v11 offset0:6 offset1:135
	v_add_u32_e32 v11, 0x1000, v10
	s_waitcnt lgkmcnt(1)
	v_cvt_pk_bf16_f32 v14, v14, v15
	s_waitcnt lgkmcnt(0)
	v_cvt_pk_bf16_f32 v15, v16, v17
	ds_read2_b32 v[16:17], v11 offset0:8 offset1:137
	v_add_u32_e32 v11, 0x1400, v10
	ds_read2_b32 v[18:19], v11 offset0:10 offset1:139
	v_add_u32_e32 v11, 0x1800, v10
	s_waitcnt lgkmcnt(1)
	v_cvt_pk_bf16_f32 v16, v16, v17
	s_waitcnt lgkmcnt(0)
	v_cvt_pk_bf16_f32 v17, v18, v19
	ds_read2_b32 v[18:19], v11 offset0:12 offset1:141
	v_add_u32_e32 v11, 0x1c00, v10
	ds_read2_b32 v[20:21], v11 offset0:14 offset1:143
	s_waitcnt lgkmcnt(1)
	v_cvt_pk_bf16_f32 v18, v18, v19
	s_waitcnt lgkmcnt(0)
	v_cvt_pk_bf16_f32 v19, v20, v21
	v_add_u32_e32 v20, s78, v8
	v_ashrrev_i32_e32 v21, 31, v20
	v_lshlrev_b64 v[20:21], 9, v[20:21]
	v_lshl_add_u64 v[20:21], s[12:13], 0, v[20:21]
	v_lshl_add_u64 v[20:21], s[34:35], 1, v[20:21]
	v_lshl_add_u64 v[20:21], v[20:21], 0, v[4:5]
	global_store_dwordx4 v[20:21], v[12:15], off
	global_store_dwordx4 v[20:21], v[16:19], off offset:16
	s_cbranch_scc1 .LBB0_30

; __device__ __forceinline__ unsigned pk_bf16(float lo, float hi) { unsigned r; asm("v_cvt_pk_bf16_f32 %0, %1, %2" : "=v"(r) : "v"(lo), "v"(hi)); return r; }
; __device__ __forceinline__ void tr_cvt(const float* __restrict__ src, int K, int N, u16* __restrict__ dst, int& base, float* tile) {
;     ...
;     for (int t = start; t < nt; t += G) {
;         const int k0 = (t / tn) << 6, n0 = (t % tn) << 7;
;         __syncthreads();
;         {
;             const int r = tid >> 5, c = (tid & 31) << 2;
;             f32x4 v[4];
; #pragma unroll
;             for (int q = 0; q < 4; ++q) v[q] = *(const f32x4*)(src + (size_t)(k0 + r + q * 16) * N + n0 + c);
; #pragma unroll
;             for (int q = 0; q < 4; ++q)
; #pragma unroll
;                 for (int e = 0; e < 4; ++e) tile[(r + q * 16) * 129 + c + e] = v[q][e];
;         }
;         __syncthreads();
;         {
;             const int n = tid >> 2, k16 = (tid & 3) << 4;
;             float v[16];
; #pragma unroll
;             for (int e = 0; e < 16; ++e) v[e] = tile[(k16 + e) * 129 + n];
;             u32x4 w0, w1;
;             w0.x = pk_bf16(v[0], v[1]); w0.y = pk_bf16(v[2], v[3]); w0.z = pk_bf16(v[4], v[5]); w0.w = pk_bf16(v[6], v[7]);
;             w1.x = pk_bf16(v[8], v[9]); w1.y = pk_bf16(v[10], v[11]); w1.z = pk_bf16(v[12], v[13]); w1.w = pk_bf16(v[14], v[15]);
;             u16* dp = dst + (size_t)(n0 + n) * K + k0 + k16;
;             *(u32x4*)dp = w0; *(u32x4*)(dp + 8) = w1;
;         }
.LBB0_33:
	s_lshr_b32 s34, s11, 31
	s_add_i32 s34, s11, s34
	s_ashr_i32 s35, s34, 1
	s_lshl_b32 s34, s35, 6
	s_lshl_b32 s35, s35, 8
	s_sub_i32 s78, s82, s35
	v_add_u32_e32 v12, s34, v2
	s_ashr_i32 s79, s78, 31
	v_ashrrev_i32_e32 v13, 31, v12
	v_lshl_add_u64 v[14:15], s[78:79], 2, v[6:7]
	v_lshlrev_b64 v[12:13], 10, v[12:13]
	v_lshl_add_u64 v[24:25], v[14:15], 0, v[12:13]
	v_add_co_u32_e32 v16, vcc, s28, v24
	s_nop 1
	v_addc_co_u32_e32 v17, vcc, 0, v25, vcc
	s_barrier
	global_load_dwordx4 v[12:15], v[24:25], off nt
	v_add_co_u32_e32 v20, vcc, s29, v24
	global_load_dwordx4 v[16:19], v[16:17], off nt
	s_nop 0
	v_addc_co_u32_e32 v21, vcc, 0, v25, vcc
	global_load_dwordx4 v[20:23], v[20:21], off nt
	v_add_co_u32_e32 v24, vcc, s30, v24
	v_add_u32_e32 v11, 0x2040, v9
	s_nop 0
	v_addc_co_u32_e32 v25, vcc, 0, v25, vcc
	global_load_dwordx4 v[24:27], v[24:25], off nt
	s_ashr_i32 s35, s34, 31
	s_add_i32 s11, s11, s33
	s_add_i32 s82, s82, s83
	s_cmp_lt_i32 s11, 8
	s_waitcnt vmcnt(3)
	ds_write2_b32 v9, v12, v13 offset1:1
	ds_write2_b32 v9, v14, v15 offset0:2 offset1:3
	s_waitcnt vmcnt(2)
	ds_write2_b32 v11, v16, v17 offset1:1
	v_add_u32_e32 v11, 0x2048, v9
	ds_write2_b32 v11, v18, v19 offset1:1
	v_add_u32_e32 v11, 0x4080, v9
	s_waitcnt vmcnt(1)
	ds_write2_b32 v11, v20, v21 offset1:1
	v_add_u32_e32 v11, 0x4088, v9
	ds_write2_b32 v11, v22, v23 offset1:1
	v_add_u32_e32 v11, 0x60c0, v9
	s_waitcnt vmcnt(0)
	ds_write2_b32 v11, v24, v25 offset1:1
	v_add_u32_e32 v11, 0x60c8, v9
	ds_write2_b32 v11, v26, v27 offset1:1
	v_add_u32_e32 v11, 0x400, v10
	s_waitcnt lgkmcnt(0)
	s_barrier
	ds_read2_b32 v[12:13], v10 offset1:129
	ds_read2_b32 v[14:15], v11 offset0:2 offset1:131
	v_add_u32_e32 v11, 0x800, v10
	s_waitcnt lgkmcnt(1)
	v_cvt_pk_bf16_f32 v12, v12, v13
	s_waitcnt lgkmcnt(0)
	v_cvt_pk_bf16_f32 v13, v14, v15
	ds_read2_b32 v[14:15], v11 offset0:4 offset1:133
	v_add_u32_e32 v11, 0xc00, v10
	ds_read2_b32 v[16:17], v11 offset0:6 offset1:135
	v_add_u32_e32 v11, 0x1000, v10
	s_waitcnt lgkmcnt(1)
	v_cvt_pk_bf16_f32 v14, v14, v15
	s_waitcnt lgkmcnt(0)
	v_cvt_pk_bf16_f32 v15, v16, v17
	ds_read2_b32 v[16:17], v11 offset0:8 offset1:137
	v_add_u32_e32 v11, 0x1400, v10
	ds_read2_b32 v[18:19], v11 offset0:10 offset1:139
	v_add_u32_e32 v11, 0x1800, v10
	s_waitcnt lgkmcnt(1)
	v_cvt_pk_bf16_f32 v16, v16, v17
	s_waitcnt lgkmcnt(0)
	v_cvt_pk_bf16_f32 v17, v18, v19
	ds_read2_b32 v[18:19], v11 offset0:12 offset1:141
	v_add_u32_e32 v11, 0x1c00, v10
	ds_read2_b32 v[20:21], v11 offset0:14 offset1:143
	s_waitcnt lgkmcnt(1)
	v_cvt_pk_bf16_f32 v18, v18, v19
	s_waitcnt lgkmcnt(0)
	v_cvt_pk_bf16_f32 v19, v20, v21
	v_add_u32_e32 v20, s78, v8
	v_ashrrev_i32_e32 v21, 31, v20
	v_lshlrev_b64 v[20:21], 9, v[20:21]
	v_lshl_add_u64 v[20:21], s[12:13], 0, v[20:21]
	v_lshl_add_u64 v[20:21], s[34:35], 1, v[20:21]
	v_lshl_add_u64 v[20:21], v[20:21], 0, v[4:5]
	global_store_dwordx4 v[20:21], v[12:15], off
	global_store_dwordx4 v[20:21], v[16:19], off offset:16
	s_cbranch_scc1 .LBB0_33

; __device__ __forceinline__ unsigned pk_bf16(float lo, float hi) { unsigned r; asm("v_cvt_pk_bf16_f32 %0, %1, %2" : "=v"(r) : "v"(lo), "v"(hi)); return r; }
; __device__ __forceinline__ void tr_cvt(const float* __restrict__ src, int K, int N, u16* __restrict__ dst, int& base, float* tile) {
;     ...
;     for (int t = start; t < nt; t += G) {
;         const int k0 = (t / tn) << 6, n0 = (t % tn) << 7;
;         __syncthreads();
;         {
;             const int r = tid >> 5, c = (tid & 31) << 2;
;             f32x4 v[4];
; #pragma unroll
;             for (int q = 0; q < 4; ++q) v[q] = *(const f32x4*)(src + (size_t)(k0 + r + q * 16) * N + n0 + c);
; #pragma unroll
;             for (int q = 0; q < 4; ++q)
; #pragma unroll
;                 for (int e = 0; e < 4; ++e) tile[(r + q * 16) * 129 + c + e] = v[q][e];
;         }
;         __syncthreads();
;         {
;             const int n = tid >> 2, k16 = (tid & 3) << 4;
;             float v[16];
; #pragma unroll
;             for (int e = 0; e < 16; ++e) v[e] = tile[(k16 + e) * 129 + n];
;             u32x4 w0, w1;
;             w0.x = pk_bf16(v[0], v[1]); w0.y = pk_bf16(v[2], v[3]); w0.z = pk_bf16(v[4], v[5]); w0.w = pk_bf16(v[6], v[7]);
;             w1.x = pk_bf16(v[8], v[9]); w1.y = pk_bf16(v[10], v[11]); w1.z = pk_bf16(v[12], v[13]); w1.w = pk_bf16(v[14], v[15]);
;             u16* dp = dst + (size_t)(n0 + n) * K + k0 + k16;
;             *(u32x4*)dp = w0; *(u32x4*)(dp + 8) = w1;
;         }
.LBB0_39:
	s_lshr_b32 s12, s78, 31
	s_add_i32 s12, s78, s12
	s_ashr_i32 s13, s12, 1
	s_lshl_b32 s12, s13, 6
	s_lshl_b32 s13, s13, 8
	s_sub_i32 s34, s79, s13
	v_add_u32_e32 v12, s12, v2
	s_ashr_i32 s35, s34, 31
	v_ashrrev_i32_e32 v13, 31, v12
	v_lshl_add_u64 v[14:15], s[34:35], 2, v[6:7]
	v_lshlrev_b64 v[12:13], 10, v[12:13]
	v_lshl_add_u64 v[24:25], v[14:15], 0, v[12:13]
	v_add_co_u32_e32 v16, vcc, s28, v24
	s_nop 1
	v_addc_co_u32_e32 v17, vcc, 0, v25, vcc
	s_barrier
	global_load_dwordx4 v[12:15], v[24:25], off nt
	v_add_co_u32_e32 v20, vcc, s29, v24
	global_load_dwordx4 v[16:19], v[16:17], off nt
	s_nop 0
	v_addc_co_u32_e32 v21, vcc, 0, v25, vcc
	global_load_dwordx4 v[20:23], v[20:21], off nt
	v_add_co_u32_e32 v24, vcc, s30, v24
	v_add_u32_e32 v11, 0x2040, v9
	s_nop 0
	v_addc_co_u32_e32 v25, vcc, 0, v25, vcc
	global_load_dwordx4 v[24:27], v[24:25], off nt
	s_ashr_i32 s13, s12, 31
	s_add_i32 s78, s78, s33
	s_add_i32 s79, s79, s82
	s_cmp_lt_i32 s78, 8
	s_waitcnt vmcnt(3)
	ds_write2_b32 v9, v12, v13 offset1:1
	ds_write2_b32 v9, v14, v15 offset0:2 offset1:3
	s_waitcnt vmcnt(2)
	ds_write2_b32 v11, v16, v17 offset1:1
	v_add_u32_e32 v11, 0x2048, v9
	ds_write2_b32 v11, v18, v19 offset1:1
	v_add_u32_e32 v11, 0x4080, v9
	s_waitcnt vmcnt(1)
	ds_write2_b32 v11, v20, v21 offset1:1
	v_add_u32_e32 v11, 0x4088, v9
	ds_write2_b32 v11, v22, v23 offset1:1
	v_add_u32_e32 v11, 0x60c0, v9
	s_waitcnt vmcnt(0)
	ds_write2_b32 v11, v24, v25 offset1:1
	v_add_u32_e32 v11, 0x60c8, v9
	ds_write2_b32 v11, v26, v27 offset1:1
	v_add_u32_e32 v11, 0x400, v10
	s_waitcnt lgkmcnt(0)
	s_barrier
	ds_read2_b32 v[12:13], v10 offset1:129
	ds_read2_b32 v[14:15], v11 offset0:2 offset1:131
	v_add_u32_e32 v11, 0x800, v10
	s_waitcnt lgkmcnt(1)
	v_cvt_pk_bf16_f32 v12, v12, v13
	s_waitcnt lgkmcnt(0)
	v_cvt_pk_bf16_f32 v13, v14, v15
	ds_read2_b32 v[14:15], v11 offset0:4 offset1:133
	v_add_u32_e32 v11, 0xc00, v10
	ds_read2_b32 v[16:17], v11 offset0:6 offset1:135
	v_add_u32_e32 v11, 0x1000, v10
	s_waitcnt lgkmcnt(1)
	v_cvt_pk_bf16_f32 v14, v14, v15
	s_waitcnt lgkmcnt(0)
	v_cvt_pk_bf16_f32 v15, v16, v17
	ds_read2_b32 v[16:17], v11 offset0:8 offset1:137
	v_add_u32_e32 v11, 0x1400, v10
	ds_read2_b32 v[18:19], v11 offset0:10 offset1:139
	v_add_u32_e32 v11, 0x1800, v10
	s_waitcnt lgkmcnt(1)
	v_cvt_pk_bf16_f32 v16, v16, v17
	s_waitcnt lgkmcnt(0)
	v_cvt_pk_bf16_f32 v17, v18, v19
	ds_read2_b32 v[18:19], v11 offset0:12 offset1:141
	v_add_u32_e32 v11, 0x1c00, v10
	ds_read2_b32 v[20:21], v11 offset0:14 offset1:143
	s_waitcnt lgkmcnt(1)
	v_cvt_pk_bf16_f32 v18, v18, v19
	s_waitcnt lgkmcnt(0)
	v_cvt_pk_bf16_f32 v19, v20, v21
	v_add_u32_e32 v20, s34, v8
	v_ashrrev_i32_e32 v21, 31, v20
	v_lshlrev_b64 v[20:21], 9, v[20:21]
	v_lshl_add_u64 v[20:21], s[10:11], 0, v[20:21]
	v_lshl_add_u64 v[20:21], s[12:13], 1, v[20:21]
	v_lshl_add_u64 v[20:21], v[20:21], 0, v[4:5]
	global_store_dwordx4 v[20:21], v[12:15], off
	global_store_dwordx4 v[20:21], v[16:19], off offset:16
	s_cbranch_scc1 .LBB0_39

; __device__ __forceinline__ unsigned pk_bf16(float lo, float hi) { unsigned r; asm("v_cvt_pk_bf16_f32 %0, %1, %2" : "=v"(r) : "v"(lo), "v"(hi)); return r; }
; __device__ __forceinline__ void tr_cvt(const float* __restrict__ src, int K, int N, u16* __restrict__ dst, int& base, float* tile) {
;     ...
;     for (int t = start; t < nt; t += G) {
;         const int k0 = (t / tn) << 6, n0 = (t % tn) << 7;
;         __syncthreads();
;         {
;             const int r = tid >> 5, c = (tid & 31) << 2;
;             f32x4 v[4];
; #pragma unroll
;             for (int q = 0; q < 4; ++q) v[q] = *(const f32x4*)(src + (size_t)(k0 + r + q * 16) * N + n0 + c);
; #pragma unroll
;             for (int q = 0; q < 4; ++q)
; #pragma unroll
;                 for (int e = 0; e < 4; ++e) tile[(r + q * 16) * 129 + c + e] = v[q][e];
;         }
;         __syncthreads();
;         {
;             const int n = tid >> 2, k16 = (tid & 3) << 4;
;             float v[16];
; #pragma unroll
;             for (int e = 0; e < 16; ++e) v[e] = tile[(k16 + e) * 129 + n];
;             u32x4 w0, w1;
;             w0.x = pk_bf16(v[0], v[1]); w0.y = pk_bf16(v[2], v[3]); w0.z = pk_bf16(v[4], v[5]); w0.w = pk_bf16(v[6], v[7]);
;             w1.x = pk_bf16(v[8], v[9]); w1.y = pk_bf16(v[10], v[11]); w1.z = pk_bf16(v[12], v[13]); w1.w = pk_bf16(v[14], v[15]);
;             u16* dp = dst + (size_t)(n0 + n) * K + k0 + k16;
;             *(u32x4*)dp = w0; *(u32x4*)(dp + 8) = w1;
;         }
.LBB0_42:
	s_ashr_i32 s34, s0, 31
	s_lshr_b32 s34, s34, 29
	s_add_i32 s34, s0, s34
	s_ashr_i32 s35, s34, 3
	s_lshl_b32 s34, s35, 6
	s_lshl_b32 s35, s35, 10
	s_sub_i32 s78, s82, s35
	v_add_u32_e32 v12, s34, v2
	s_ashr_i32 s79, s78, 31
	v_ashrrev_i32_e32 v13, 31, v12
	v_lshl_add_u64 v[14:15], s[78:79], 2, v[6:7]
	v_lshlrev_b64 v[12:13], 12, v[12:13]
	v_lshl_add_u64 v[24:25], v[14:15], 0, v[12:13]
	v_add_co_u32_e32 v16, vcc, s31, v24
	s_nop 1
	v_addc_co_u32_e32 v17, vcc, 0, v25, vcc
	s_barrier
	global_load_dwordx4 v[12:15], v[24:25], off nt
	v_add_co_u32_e32 v20, vcc, s24, v24
	global_load_dwordx4 v[16:19], v[16:17], off nt
	s_nop 0
	v_addc_co_u32_e32 v21, vcc, 0, v25, vcc
	global_load_dwordx4 v[20:23], v[20:21], off nt
	v_add_co_u32_e32 v24, vcc, s80, v24
	v_add_u32_e32 v11, 0x2040, v9
	s_nop 0
	v_addc_co_u32_e32 v25, vcc, 0, v25, vcc
	global_load_dwordx4 v[24:27], v[24:25], off nt
	s_ashr_i32 s35, s34, 31
	s_add_i32 s0, s0, s33
	s_add_i32 s82, s82, s83
	s_cmp_lt_i32 s0, 8
	s_waitcnt vmcnt(3)
	ds_write2_b32 v9, v12, v13 offset1:1
	ds_write2_b32 v9, v14, v15 offset0:2 offset1:3
	s_waitcnt vmcnt(2)
	ds_write2_b32 v11, v16, v17 offset1:1
	v_add_u32_e32 v11, 0x2048, v9
	ds_write2_b32 v11, v18, v19 offset1:1
	v_add_u32_e32 v11, 0x4080, v9
	s_waitcnt vmcnt(1)
	ds_write2_b32 v11, v20, v21 offset1:1
	v_add_u32_e32 v11, 0x4088, v9
	ds_write2_b32 v11, v22, v23 offset1:1
	v_add_u32_e32 v11, 0x60c0, v9
	s_waitcnt vmcnt(0)
	ds_write2_b32 v11, v24, v25 offset1:1
	v_add_u32_e32 v11, 0x60c8, v9
	ds_write2_b32 v11, v26, v27 offset1:1
	v_add_u32_e32 v11, 0x400, v10
	s_waitcnt lgkmcnt(0)
	s_barrier
	ds_read2_b32 v[12:13], v10 offset1:129
	ds_read2_b32 v[14:15], v11 offset0:2 offset1:131
	v_add_u32_e32 v11, 0x800, v10
	s_waitcnt lgkmcnt(1)
	v_cvt_pk_bf16_f32 v12, v12, v13
	s_waitcnt lgkmcnt(0)
	v_cvt_pk_bf16_f32 v13, v14, v15
	ds_read2_b32 v[14:15], v11 offset0:4 offset1:133
	v_add_u32_e32 v11, 0xc00, v10
	ds_read2_b32 v[16:17], v11 offset0:6 offset1:135
	v_add_u32_e32 v11, 0x1000, v10
	s_waitcnt lgkmcnt(1)
	v_cvt_pk_bf16_f32 v14, v14, v15
	s_waitcnt lgkmcnt(0)
	v_cvt_pk_bf16_f32 v15, v16, v17
	ds_read2_b32 v[16:17], v11 offset0:8 offset1:137
	v_add_u32_e32 v11, 0x1400, v10
	ds_read2_b32 v[18:19], v11 offset0:10 offset1:139
	v_add_u32_e32 v11, 0x1800, v10
	s_waitcnt lgkmcnt(1)
	v_cvt_pk_bf16_f32 v16, v16, v17
	s_waitcnt lgkmcnt(0)
	v_cvt_pk_bf16_f32 v17, v18, v19
	ds_read2_b32 v[18:19], v11 offset0:12 offset1:141
	v_add_u32_e32 v11, 0x1c00, v10
	ds_read2_b32 v[20:21], v11 offset0:14 offset1:143
	s_waitcnt lgkmcnt(1)
	v_cvt_pk_bf16_f32 v18, v18, v19
	s_waitcnt lgkmcnt(0)
	v_cvt_pk_bf16_f32 v19, v20, v21
	v_add_u32_e32 v20, s78, v8
	v_ashrrev_i32_e32 v21, 31, v20
	v_lshlrev_b64 v[20:21], 7, v[20:21]
	v_lshl_add_u64 v[20:21], s[12:13], 0, v[20:21]
	v_lshl_add_u64 v[20:21], s[34:35], 1, v[20:21]
	v_lshl_add_u64 v[20:21], v[20:21], 0, v[4:5]
	global_store_dwordx4 v[20:21], v[12:15], off
	global_store_dwordx4 v[20:21], v[16:19], off offset:16
	s_cbranch_scc1 .LBB0_42

; __device__ __forceinline__ unsigned pk_bf16(float lo, float hi) { unsigned r; asm("v_cvt_pk_bf16_f32 %0, %1, %2" : "=v"(r) : "v"(lo), "v"(hi)); return r; }
; __device__ __forceinline__ void tr_cvt(const float* __restrict__ src, int K, int N, u16* __restrict__ dst, int& base, float* tile) {
;     ...
;     for (int t = start; t < nt; t += G) {
;         const int k0 = (t / tn) << 6, n0 = (t % tn) << 7;
;         __syncthreads();
;         {
;             const int r = tid >> 5, c = (tid & 31) << 2;
;             f32x4 v[4];
; #pragma unroll
;             for (int q = 0; q < 4; ++q) v[q] = *(const f32x4*)(src + (size_t)(k0 + r + q * 16) * N + n0 + c);
; #pragma unroll
;             for (int q = 0; q < 4; ++q)
; #pragma unroll
;                 for (int e = 0; e < 4; ++e) tile[(r + q * 16) * 129 + c + e] = v[q][e];
;         }
;         __syncthreads();
;         {
;             const int n = tid >> 2, k16 = (tid & 3) << 4;
;             float v[16];
; #pragma unroll
;             for (int e = 0; e < 16; ++e) v[e] = tile[(k16 + e) * 129 + n];
;             u32x4 w0, w1;
;             w0.x = pk_bf16(v[0], v[1]); w0.y = pk_bf16(v[2], v[3]); w0.z = pk_bf16(v[4], v[5]); w0.w = pk_bf16(v[6], v[7]);
;             w1.x = pk_bf16(v[8], v[9]); w1.y = pk_bf16(v[10], v[11]); w1.z = pk_bf16(v[12], v[13]); w1.w = pk_bf16(v[14], v[15]);
;             u16* dp = dst + (size_t)(n0 + n) * K + k0 + k16;
;             *(u32x4*)dp = w0; *(u32x4*)(dp + 8) = w1;
;         }
;     }
;     base += nt;
.LBB0_45:
	s_ashr_i32 s10, s0, 31
	s_lshr_b32 s10, s10, 29
	s_add_i32 s10, s0, s10
	s_ashr_i32 s11, s10, 3
	s_lshl_b32 s10, s11, 6
	s_lshl_b32 s11, s11, 10
	s_sub_i32 s34, s78, s11
	v_add_u32_e32 v12, s10, v2
	s_ashr_i32 s35, s34, 31
	v_ashrrev_i32_e32 v13, 31, v12
	v_lshl_add_u64 v[14:15], s[34:35], 2, v[6:7]
	v_lshlrev_b64 v[12:13], 12, v[12:13]
	v_lshl_add_u64 v[24:25], v[14:15], 0, v[12:13]
	v_add_co_u32_e32 v16, vcc, s31, v24
	s_nop 1
	v_addc_co_u32_e32 v17, vcc, 0, v25, vcc
	s_barrier
	global_load_dwordx4 v[12:15], v[24:25], off nt
	v_add_co_u32_e32 v20, vcc, s24, v24
	global_load_dwordx4 v[16:19], v[16:17], off nt
	s_nop 0
	v_addc_co_u32_e32 v21, vcc, 0, v25, vcc
	global_load_dwordx4 v[20:23], v[20:21], off nt
	v_add_co_u32_e32 v24, vcc, s80, v24
	v_add_u32_e32 v11, 0x2040, v9
	s_nop 0
	v_addc_co_u32_e32 v25, vcc, 0, v25, vcc
	global_load_dwordx4 v[24:27], v[24:25], off nt
	s_ashr_i32 s11, s10, 31
	s_add_i32 s0, s0, s33
	s_add_i32 s78, s78, s79
	s_cmp_lt_i32 s0, 8
	s_waitcnt vmcnt(3)
	ds_write2_b32 v9, v12, v13 offset1:1
	ds_write2_b32 v9, v14, v15 offset0:2 offset1:3
	s_waitcnt vmcnt(2)
	ds_write2_b32 v11, v16, v17 offset1:1
	v_add_u32_e32 v11, 0x2048, v9
	ds_write2_b32 v11, v18, v19 offset1:1
	v_add_u32_e32 v11, 0x4080, v9
	s_waitcnt vmcnt(1)
	ds_write2_b32 v11, v20, v21 offset1:1
	v_add_u32_e32 v11, 0x4088, v9
	ds_write2_b32 v11, v22, v23 offset1:1
	v_add_u32_e32 v11, 0x60c0, v9
	s_waitcnt vmcnt(0)
	ds_write2_b32 v11, v24, v25 offset1:1
	v_add_u32_e32 v11, 0x60c8, v9
	ds_write2_b32 v11, v26, v27 offset1:1
	v_add_u32_e32 v11, 0x400, v10
	s_waitcnt lgkmcnt(0)
	s_barrier
	ds_read2_b32 v[12:13], v10 offset1:129
	ds_read2_b32 v[14:15], v11 offset0:2 offset1:131
	v_add_u32_e32 v11, 0x800, v10
	s_waitcnt lgkmcnt(1)
	v_cvt_pk_bf16_f32 v12, v12, v13
	s_waitcnt lgkmcnt(0)
	v_cvt_pk_bf16_f32 v13, v14, v15
	ds_read2_b32 v[14:15], v11 offset0:4 offset1:133
	v_add_u32_e32 v11, 0xc00, v10
	ds_read2_b32 v[16:17], v11 offset0:6 offset1:135
	v_add_u32_e32 v11, 0x1000, v10
	s_waitcnt lgkmcnt(1)
	v_cvt_pk_bf16_f32 v14, v14, v15
	s_waitcnt lgkmcnt(0)
	v_cvt_pk_bf16_f32 v15, v16, v17
	ds_read2_b32 v[16:17], v11 offset0:8 offset1:137
	v_add_u32_e32 v11, 0x1400, v10
	ds_read2_b32 v[18:19], v11 offset0:10 offset1:139
	v_add_u32_e32 v11, 0x1800, v10
	s_waitcnt lgkmcnt(1)
	v_cvt_pk_bf16_f32 v16, v16, v17
	s_waitcnt lgkmcnt(0)
	v_cvt_pk_bf16_f32 v17, v18, v19
	ds_read2_b32 v[18:19], v11 offset0:12 offset1:141
	v_add_u32_e32 v11, 0x1c00, v10
	ds_read2_b32 v[20:21], v11 offset0:14 offset1:143
	s_waitcnt lgkmcnt(1)
	v_cvt_pk_bf16_f32 v18, v18, v19
	s_waitcnt lgkmcnt(0)
	v_cvt_pk_bf16_f32 v19, v20, v21
	v_add_u32_e32 v20, s34, v8
	v_ashrrev_i32_e32 v21, 31, v20
	v_lshlrev_b64 v[20:21], 7, v[20:21]
	v_lshl_add_u64 v[20:21], s[12:13], 0, v[20:21]
	v_lshl_add_u64 v[20:21], s[10:11], 1, v[20:21]
	v_lshl_add_u64 v[20:21], v[20:21], 0, v[4:5]
	global_store_dwordx4 v[20:21], v[12:15], off
	global_store_dwordx4 v[20:21], v[16:19], off offset:16
	s_cbranch_scc1 .LBB0_45
	s_branch .LBB0_12
